# stick-breaking unit: the eight epilogue gate loads issued with the Q loads (held in v216-v247 across the key loop)
# baseline (speedup 1.0000x reference)
.LBB0_308:
	s_add_u32 s4, s24, s26
	s_addc_u32 s5, s25, s27
	s_lshl_b64 s[0:1], s[28:29], 25
	s_add_u32 s0, s90, s0
	s_addc_u32 s1, s91, s1
	s_waitcnt vmcnt(0)
	s_barrier
	s_add_u32 s0, s0, s26
	s_addc_u32 s1, s1, s27
	s_setprio 0
	v_lshl_add_u64 v[64:65], s[4:5], 0, v[134:135]
	v_lshlrev_b32_e32 v120, 1, v140
	v_lshl_add_u64 v[64:65], v[64:65], 0, v[120:121]
	v_add_co_u32_e32 v66, vcc, s54, v64
	v_lshl_add_u64 v[90:91], v[64:65], 0, s[8:9]
	s_nop 0
	v_addc_co_u32_e32 v67, vcc, 0, v65, vcc
	v_mov_b64_e32 v[78:79], v[216:217]
	v_mov_b64_e32 v[80:81], v[218:219]
	v_mov_b64_e32 v[82:83], v[220:221]
	v_mov_b64_e32 v[84:85], v[222:223]
	v_lshlrev_b64 v[64:65], 12, v[122:123]
	v_pk_mul_f32 v[92:93], v[48:49], s[12:13] op_sel_hi:[1,0]
	v_lshl_add_u64 v[48:49], s[0:1], 0, v[64:65]
	v_pk_mul_f32 v[94:95], v[50:51], s[12:13] op_sel_hi:[1,0]
	v_pk_mul_f32 v[96:97], v[52:53], s[12:13] op_sel_hi:[1,0]
	v_pk_mul_f32 v[98:99], v[54:55], s[12:13] op_sel_hi:[1,0]
	v_lshl_add_u64 v[76:77], v[48:49], 0, v[120:121]
	v_mov_b64_e32 v[86:87], v[224:225]
	v_mov_b64_e32 v[88:89], v[226:227]
	v_mov_b64_e32 v[72:73], v[228:229]
	v_mov_b64_e32 v[74:75], v[230:231]
	v_mov_b64_e32 v[68:69], v[232:233]
	v_mov_b64_e32 v[70:71], v[234:235]
	v_mov_b64_e32 v[64:65], v[236:237]
	v_mov_b64_e32 v[66:67], v[238:239]
	v_mov_b64_e32 v[52:53], v[240:241]
	v_mov_b64_e32 v[54:55], v[242:243]
	v_mov_b64_e32 v[48:49], v[244:245]
	v_mov_b64_e32 v[50:51], v[246:247]
	v_pk_mul_f32 v[56:57], v[56:57], s[12:13] op_sel_hi:[1,0]
	v_pk_mul_f32 v[58:59], v[58:59], s[12:13] op_sel_hi:[1,0]
	v_pk_mul_f32 v[60:61], v[60:61], s[12:13] op_sel_hi:[1,0]
	v_pk_mul_f32 v[32:33], v[32:33], s[12:13] op_sel_hi:[1,0]
	v_pk_mul_f32 v[34:35], v[34:35], s[12:13] op_sel_hi:[1,0]
	v_pk_mul_f32 v[36:37], v[36:37], s[12:13] op_sel_hi:[1,0]
	v_pk_mul_f32 v[16:17], v[16:17], s[12:13] op_sel_hi:[1,0]
	v_pk_mul_f32 v[18:19], v[18:19], s[12:13] op_sel_hi:[1,0]
	v_pk_mul_f32 v[20:21], v[20:21], s[12:13] op_sel_hi:[1,0]
	v_pk_mul_f32 v[0:1], v[0:1], s[12:13] op_sel_hi:[1,0]
	v_pk_mul_f32 v[2:3], v[2:3], s[12:13] op_sel_hi:[1,0]
	v_pk_mul_f32 v[4:5], v[4:5], s[12:13] op_sel_hi:[1,0]
	s_mov_b64 s[0:1], 0
	s_waitcnt vmcnt(0)
	v_mov_b32_e32 v90, v80
	v_mov_b32_e32 v91, v81
	v_mov_b32_e32 v112, v84
	v_permlane32_swap_b32_e32 v78, v90
	v_permlane32_swap_b32_e32 v79, v91
	v_mov_b32_e32 v113, v85
	v_permlane32_swap_b32_e32 v82, v112
	v_lshlrev_b32_e32 v80, 16, v78
	v_and_b32_e32 v81, 0xffff0000, v78
	v_lshlrev_b32_e32 v78, 16, v79
	v_and_b32_e32 v79, 0xffff0000, v79
	v_lshlrev_b32_e32 v84, 16, v90
	v_and_b32_e32 v85, 0xffff0000, v90
	v_lshlrev_b32_e32 v90, 16, v91
	v_and_b32_e32 v91, 0xffff0000, v91
	v_lshlrev_b32_e32 v100, 16, v82
	v_and_b32_e32 v101, 0xffff0000, v82
	v_mul_f32_e32 v82, 0xbfb8aa3b, v80
	v_mul_f32_e32 v102, 0xbfb8aa3b, v81
	v_mul_f32_e32 v103, 0xbfb8aa3b, v78
	v_mul_f32_e32 v104, 0xbfb8aa3b, v79
	v_mul_f32_e32 v105, 0xbfb8aa3b, v84
	v_mul_f32_e32 v106, 0xbfb8aa3b, v85
	v_mul_f32_e32 v107, 0xbfb8aa3b, v90
	v_mul_f32_e32 v108, 0xbfb8aa3b, v91
	v_mul_f32_e32 v109, 0xbfb8aa3b, v100
	v_exp_f32_e32 v82, v82
	v_exp_f32_e32 v102, v102
	v_exp_f32_e32 v103, v103
	v_exp_f32_e32 v104, v104
	v_exp_f32_e32 v105, v105
	v_exp_f32_e32 v106, v106
	v_exp_f32_e32 v107, v107
	v_exp_f32_e32 v108, v108
	v_exp_f32_e32 v109, v109
	v_mul_f32_e32 v110, 0xbfb8aa3b, v101
	v_exp_f32_e32 v111, v110
	v_add_f32_e32 v82, 1.0, v82
	v_add_f32_e32 v110, 1.0, v102
	v_add_f32_e32 v114, 1.0, v103
	v_add_f32_e32 v115, 1.0, v104
	v_add_f32_e32 v116, 1.0, v105
	v_add_f32_e32 v117, 1.0, v106
	v_add_f32_e32 v118, 1.0, v107
	v_add_f32_e32 v119, 1.0, v108
	v_add_f32_e32 v120, 1.0, v109
	v_rcp_f32_e32 v102, v82
	v_rcp_f32_e32 v103, v110
	v_rcp_f32_e32 v104, v114
	v_rcp_f32_e32 v105, v115
	v_rcp_f32_e32 v106, v116
	v_rcp_f32_e32 v107, v117
	v_rcp_f32_e32 v108, v118
	v_rcp_f32_e32 v109, v119
	v_pk_mul_f32 v[80:81], v[102:103], v[80:81]
	v_pk_mul_f32 v[78:79], v[104:105], v[78:79]
	v_pk_mul_f32 v[84:85], v[106:107], v[84:85]
	v_pk_mul_f32 v[90:91], v[108:109], v[90:91]
	v_pk_mul_f32 v[80:81], v[92:93], v[80:81]
	v_pk_mul_f32 v[92:93], v[94:95], v[78:79]
	v_pk_mul_f32 v[84:85], v[96:97], v[84:85]
	v_pk_mul_f32 v[90:91], v[98:99], v[90:91]
	v_cvt_pk_bf16_f32 v78, v80, v81
	v_cvt_pk_bf16_f32 v79, v92, v93
	v_cvt_pk_bf16_f32 v80, v84, v85
	v_cvt_pk_bf16_f32 v81, v90, v91
	s_nop 0
	v_permlane32_swap_b32_e32 v78, v80
	v_permlane32_swap_b32_e32 v79, v81
	v_permlane32_swap_b32_e32 v83, v113
	global_store_dwordx4 v[76:77], v[78:81], off
	v_rcp_f32_e32 v110, v120
	s_nop 0
	v_add_f32_e32 v78, 1.0, v111
	v_rcp_f32_e32 v111, v78
	v_lshlrev_b32_e32 v78, 16, v83
	v_and_b32_e32 v79, 0xffff0000, v83
	v_mul_f32_e32 v80, 0xbfb8aa3b, v78
	v_exp_f32_e32 v82, v80
	v_mul_f32_e32 v80, 0xbfb8aa3b, v79
	v_exp_f32_e32 v83, v80
	v_pk_mul_f32 v[80:81], v[110:111], v[100:101]
	v_add_f32_e32 v82, 1.0, v82
	v_rcp_f32_e32 v82, v82
	v_add_f32_e32 v83, 1.0, v83
	v_rcp_f32_e32 v83, v83
	v_pk_mul_f32 v[56:57], v[56:57], v[80:81]
	v_lshlrev_b32_e32 v80, 16, v113
	v_cvt_pk_bf16_f32 v56, v56, v57
	v_pk_mul_f32 v[78:79], v[82:83], v[78:79]
	v_and_b32_e32 v81, 0xffff0000, v113
	v_pk_mul_f32 v[58:59], v[58:59], v[78:79]
	v_mul_f32_e32 v82, 0xbfb8aa3b, v80
	v_cvt_pk_bf16_f32 v57, v58, v59
	v_lshlrev_b32_e32 v58, 16, v112
	v_mul_f32_e32 v59, 0xbfb8aa3b, v58
	v_exp_f32_e32 v78, v59
	v_and_b32_e32 v59, 0xffff0000, v112
	v_mul_f32_e32 v79, 0xbfb8aa3b, v59
	v_exp_f32_e32 v79, v79
	v_add_f32_e32 v78, 1.0, v78
	v_mul_f32_e32 v83, 0xbfb8aa3b, v81
	v_rcp_f32_e32 v78, v78
	v_add_f32_e32 v79, 1.0, v79
	v_rcp_f32_e32 v79, v79
	v_exp_f32_e32 v82, v82
	v_exp_f32_e32 v83, v83
	v_pk_mul_f32 v[58:59], v[78:79], v[58:59]
	v_add_f32_e32 v78, 1.0, v82
	v_add_f32_e32 v79, 1.0, v83
	v_rcp_f32_e32 v78, v78
	v_rcp_f32_e32 v79, v79
	v_pk_mul_f32 v[58:59], v[60:61], v[58:59]
	v_pk_mul_f32 v[60:61], v[62:63], s[12:13] op_sel_hi:[1,0]
	v_cvt_pk_bf16_f32 v58, v58, v59
	v_pk_mul_f32 v[62:63], v[78:79], v[80:81]
	s_nop 0
	v_permlane32_swap_b32_e32 v56, v58
	v_pk_mul_f32 v[60:61], v[60:61], v[62:63]
	v_mov_b32_e32 v62, v88
	v_cvt_pk_bf16_f32 v59, v60, v61
	s_nop 1
	v_permlane32_swap_b32_e32 v57, v59
	v_permlane32_swap_b32_e32 v86, v62
	global_store_dwordx4 v[76:77], v[56:59], off offset:32
	v_mov_b32_e32 v63, v89
	s_nop 1
	v_permlane32_swap_b32_e32 v87, v63
	v_lshlrev_b32_e32 v56, 16, v86
	v_mul_f32_e32 v57, 0xbfb8aa3b, v56
	v_exp_f32_e32 v58, v57
	v_and_b32_e32 v57, 0xffff0000, v86
	v_mul_f32_e32 v59, 0xbfb8aa3b, v57
	v_exp_f32_e32 v59, v59
	v_lshlrev_b32_e32 v60, 16, v87
	v_and_b32_e32 v61, 0xffff0000, v87
	v_add_f32_e32 v58, 1.0, v58
	v_add_f32_e32 v59, 1.0, v59
	v_mul_f32_e32 v78, 0xbfb8aa3b, v60
	v_mul_f32_e32 v79, 0xbfb8aa3b, v61
	v_rcp_f32_e32 v58, v58
	v_rcp_f32_e32 v59, v59
	v_exp_f32_e32 v78, v78
	v_exp_f32_e32 v79, v79
	v_pk_mul_f32 v[56:57], v[58:59], v[56:57]
	v_add_f32_e32 v58, 1.0, v78
	v_add_f32_e32 v59, 1.0, v79
	v_rcp_f32_e32 v58, v58
	v_rcp_f32_e32 v59, v59
	v_pk_mul_f32 v[32:33], v[32:33], v[56:57]
	v_pk_mul_f32 v[56:57], v[58:59], v[60:61]
	s_nop 0
	v_pk_mul_f32 v[34:35], v[34:35], v[56:57]
	v_cvt_pk_bf16_f32 v32, v32, v33
	v_cvt_pk_bf16_f32 v33, v34, v35
	v_lshlrev_b32_e32 v34, 16, v62
	v_mul_f32_e32 v35, 0xbfb8aa3b, v34
	v_exp_f32_e32 v56, v35
	v_and_b32_e32 v35, 0xffff0000, v62
	v_mul_f32_e32 v57, 0xbfb8aa3b, v35
	v_exp_f32_e32 v57, v57
	v_lshlrev_b32_e32 v58, 16, v63
	v_and_b32_e32 v59, 0xffff0000, v63
	v_add_f32_e32 v56, 1.0, v56
	v_add_f32_e32 v57, 1.0, v57
	v_mul_f32_e32 v60, 0xbfb8aa3b, v58
	v_mul_f32_e32 v61, 0xbfb8aa3b, v59
	v_rcp_f32_e32 v56, v56
	v_rcp_f32_e32 v57, v57
	v_exp_f32_e32 v60, v60
	v_exp_f32_e32 v61, v61
	v_pk_mul_f32 v[34:35], v[56:57], v[34:35]
	v_add_f32_e32 v56, 1.0, v60
	v_add_f32_e32 v57, 1.0, v61
	v_rcp_f32_e32 v56, v56
	v_rcp_f32_e32 v57, v57
	v_pk_mul_f32 v[34:35], v[36:37], v[34:35]
	v_pk_mul_f32 v[36:37], v[38:39], s[12:13] op_sel_hi:[1,0]
	v_cvt_pk_bf16_f32 v34, v34, v35
	v_pk_mul_f32 v[38:39], v[56:57], v[58:59]
	v_mov_b32_e32 v56, v74
	v_pk_mul_f32 v[36:37], v[36:37], v[38:39]
	v_permlane32_swap_b32_e32 v32, v34
	v_cvt_pk_bf16_f32 v35, v36, v37
	s_nop 1
	v_permlane32_swap_b32_e32 v33, v35
	v_permlane32_swap_b32_e32 v72, v56
	global_store_dwordx4 v[76:77], v[32:35], off offset:64
	v_mov_b32_e32 v57, v75
	s_nop 1
	v_permlane32_swap_b32_e32 v73, v57
	v_lshlrev_b32_e32 v32, 16, v72
	v_mul_f32_e32 v33, 0xbfb8aa3b, v32
	v_exp_f32_e32 v34, v33
	v_and_b32_e32 v33, 0xffff0000, v72
	v_mul_f32_e32 v35, 0xbfb8aa3b, v33
	v_exp_f32_e32 v35, v35
	v_lshlrev_b32_e32 v38, 16, v73
	v_and_b32_e32 v39, 0xffff0000, v73
	v_add_f32_e32 v34, 1.0, v34
	v_pk_mul_f32 v[36:37], v[40:41], s[12:13] op_sel_hi:[1,0]
	v_add_f32_e32 v35, 1.0, v35
	v_mul_f32_e32 v40, 0xbfb8aa3b, v38
	v_mul_f32_e32 v41, 0xbfb8aa3b, v39
	v_rcp_f32_e32 v34, v34
	v_rcp_f32_e32 v35, v35
	v_exp_f32_e32 v40, v40
	v_exp_f32_e32 v41, v41
	v_pk_mul_f32 v[32:33], v[34:35], v[32:33]
	v_add_f32_e32 v34, 1.0, v40
	v_add_f32_e32 v35, 1.0, v41
	v_rcp_f32_e32 v34, v34
	v_rcp_f32_e32 v35, v35
	v_pk_mul_f32 v[32:33], v[36:37], v[32:33]
	v_pk_mul_f32 v[36:37], v[42:43], s[12:13] op_sel_hi:[1,0]
	v_cvt_pk_bf16_f32 v32, v32, v33
	v_pk_mul_f32 v[34:35], v[34:35], v[38:39]
	v_lshlrev_b32_e32 v40, 16, v57
	v_pk_mul_f32 v[34:35], v[36:37], v[34:35]
	v_and_b32_e32 v41, 0xffff0000, v57
	v_cvt_pk_bf16_f32 v33, v34, v35
	v_lshlrev_b32_e32 v34, 16, v56
	v_mul_f32_e32 v35, 0xbfb8aa3b, v34
	v_exp_f32_e32 v36, v35
	v_and_b32_e32 v35, 0xffff0000, v56
	v_mul_f32_e32 v37, 0xbfb8aa3b, v35
	v_exp_f32_e32 v37, v37
	v_add_f32_e32 v36, 1.0, v36
	v_mul_f32_e32 v42, 0xbfb8aa3b, v40
	v_mul_f32_e32 v43, 0xbfb8aa3b, v41
	v_add_f32_e32 v37, 1.0, v37
	v_rcp_f32_e32 v36, v36
	v_rcp_f32_e32 v37, v37
	v_exp_f32_e32 v42, v42
	v_exp_f32_e32 v43, v43
	v_pk_mul_f32 v[38:39], v[44:45], s[12:13] op_sel_hi:[1,0]
	v_pk_mul_f32 v[34:35], v[36:37], v[34:35]
	v_add_f32_e32 v36, 1.0, v42
	v_add_f32_e32 v37, 1.0, v43
	v_rcp_f32_e32 v36, v36
	v_rcp_f32_e32 v37, v37
	v_pk_mul_f32 v[34:35], v[38:39], v[34:35]
	v_pk_mul_f32 v[38:39], v[46:47], s[12:13] op_sel_hi:[1,0]
	v_cvt_pk_bf16_f32 v34, v34, v35
	v_pk_mul_f32 v[36:37], v[36:37], v[40:41]
	s_nop 0
	v_permlane32_swap_b32_e32 v32, v34
	v_pk_mul_f32 v[36:37], v[38:39], v[36:37]
	v_mov_b32_e32 v38, v70
	v_cvt_pk_bf16_f32 v35, v36, v37
	s_nop 1
	v_permlane32_swap_b32_e32 v33, v35
	v_permlane32_swap_b32_e32 v68, v38
	global_store_dwordx4 v[76:77], v[32:35], off offset:96
	v_mov_b32_e32 v39, v71
	s_nop 1
	v_permlane32_swap_b32_e32 v69, v39
	v_lshlrev_b32_e32 v32, 16, v68
	v_mul_f32_e32 v33, 0xbfb8aa3b, v32
	v_exp_f32_e32 v34, v33
	v_and_b32_e32 v33, 0xffff0000, v68
	v_mul_f32_e32 v35, 0xbfb8aa3b, v33
	v_exp_f32_e32 v35, v35
	v_lshlrev_b32_e32 v36, 16, v69
	v_and_b32_e32 v37, 0xffff0000, v69
	v_add_f32_e32 v34, 1.0, v34
	v_add_f32_e32 v35, 1.0, v35
	v_mul_f32_e32 v40, 0xbfb8aa3b, v36
	v_mul_f32_e32 v41, 0xbfb8aa3b, v37
	v_rcp_f32_e32 v34, v34
	v_rcp_f32_e32 v35, v35
	v_exp_f32_e32 v40, v40
	v_exp_f32_e32 v41, v41
	v_pk_mul_f32 v[32:33], v[34:35], v[32:33]
	v_add_f32_e32 v34, 1.0, v40
	v_add_f32_e32 v35, 1.0, v41
	v_rcp_f32_e32 v34, v34
	v_rcp_f32_e32 v35, v35
	v_pk_mul_f32 v[16:17], v[16:17], v[32:33]
	v_pk_mul_f32 v[32:33], v[34:35], v[36:37]
	s_nop 0
	v_pk_mul_f32 v[18:19], v[18:19], v[32:33]
	v_cvt_pk_bf16_f32 v16, v16, v17
	v_cvt_pk_bf16_f32 v17, v18, v19
	v_lshlrev_b32_e32 v18, 16, v38
	v_mul_f32_e32 v19, 0xbfb8aa3b, v18
	v_exp_f32_e32 v32, v19
	v_and_b32_e32 v19, 0xffff0000, v38
	v_mul_f32_e32 v33, 0xbfb8aa3b, v19
	v_exp_f32_e32 v33, v33
	v_lshlrev_b32_e32 v34, 16, v39
	v_and_b32_e32 v35, 0xffff0000, v39
	v_add_f32_e32 v32, 1.0, v32
	v_add_f32_e32 v33, 1.0, v33
	v_mul_f32_e32 v36, 0xbfb8aa3b, v34
	v_mul_f32_e32 v37, 0xbfb8aa3b, v35
	v_rcp_f32_e32 v32, v32
	v_rcp_f32_e32 v33, v33
	v_exp_f32_e32 v36, v36
	v_exp_f32_e32 v37, v37
	v_pk_mul_f32 v[18:19], v[32:33], v[18:19]
	v_add_f32_e32 v32, 1.0, v36
	v_add_f32_e32 v33, 1.0, v37
	v_rcp_f32_e32 v32, v32
	v_rcp_f32_e32 v33, v33
	v_pk_mul_f32 v[18:19], v[20:21], v[18:19]
	v_pk_mul_f32 v[20:21], v[22:23], s[12:13] op_sel_hi:[1,0]
	v_cvt_pk_bf16_f32 v18, v18, v19
	v_pk_mul_f32 v[22:23], v[32:33], v[34:35]
	v_mov_b32_e32 v32, v66
	v_pk_mul_f32 v[20:21], v[20:21], v[22:23]
	v_permlane32_swap_b32_e32 v16, v18
	v_cvt_pk_bf16_f32 v19, v20, v21
	s_nop 1
	v_permlane32_swap_b32_e32 v17, v19
	v_permlane32_swap_b32_e32 v64, v32
	global_store_dwordx4 v[76:77], v[16:19], off offset:128
	v_mov_b32_e32 v33, v67
	s_nop 1
	v_permlane32_swap_b32_e32 v65, v33
	v_lshlrev_b32_e32 v16, 16, v64
	v_mul_f32_e32 v17, 0xbfb8aa3b, v16
	v_exp_f32_e32 v18, v17
	v_and_b32_e32 v17, 0xffff0000, v64
	v_mul_f32_e32 v19, 0xbfb8aa3b, v17
	v_exp_f32_e32 v19, v19
	v_lshlrev_b32_e32 v22, 16, v65
	v_and_b32_e32 v23, 0xffff0000, v65
	v_add_f32_e32 v18, 1.0, v18
	v_pk_mul_f32 v[20:21], v[24:25], s[12:13] op_sel_hi:[1,0]
	v_add_f32_e32 v19, 1.0, v19
	v_mul_f32_e32 v24, 0xbfb8aa3b, v22
	v_mul_f32_e32 v25, 0xbfb8aa3b, v23
	v_rcp_f32_e32 v18, v18
	v_rcp_f32_e32 v19, v19
	v_exp_f32_e32 v24, v24
	v_exp_f32_e32 v25, v25
	v_pk_mul_f32 v[16:17], v[18:19], v[16:17]
	v_add_f32_e32 v18, 1.0, v24
	v_add_f32_e32 v19, 1.0, v25
	v_rcp_f32_e32 v18, v18
	v_rcp_f32_e32 v19, v19
	v_pk_mul_f32 v[16:17], v[20:21], v[16:17]
	v_pk_mul_f32 v[20:21], v[26:27], s[12:13] op_sel_hi:[1,0]
	v_cvt_pk_bf16_f32 v16, v16, v17
	v_pk_mul_f32 v[18:19], v[18:19], v[22:23]
	v_lshlrev_b32_e32 v24, 16, v33
	v_pk_mul_f32 v[18:19], v[20:21], v[18:19]
	v_and_b32_e32 v25, 0xffff0000, v33
	v_cvt_pk_bf16_f32 v17, v18, v19
	v_lshlrev_b32_e32 v18, 16, v32
	v_mul_f32_e32 v19, 0xbfb8aa3b, v18
	v_exp_f32_e32 v20, v19
	v_and_b32_e32 v19, 0xffff0000, v32
	v_mul_f32_e32 v21, 0xbfb8aa3b, v19
	v_exp_f32_e32 v21, v21
	v_add_f32_e32 v20, 1.0, v20
	v_mul_f32_e32 v26, 0xbfb8aa3b, v24
	v_mul_f32_e32 v27, 0xbfb8aa3b, v25
	v_add_f32_e32 v21, 1.0, v21
	v_rcp_f32_e32 v20, v20
	v_rcp_f32_e32 v21, v21
	v_exp_f32_e32 v26, v26
	v_exp_f32_e32 v27, v27
	v_pk_mul_f32 v[22:23], v[28:29], s[12:13] op_sel_hi:[1,0]
	v_pk_mul_f32 v[18:19], v[20:21], v[18:19]
	v_add_f32_e32 v20, 1.0, v26
	v_add_f32_e32 v21, 1.0, v27
	v_rcp_f32_e32 v20, v20
	v_rcp_f32_e32 v21, v21
	v_pk_mul_f32 v[18:19], v[22:23], v[18:19]
	v_pk_mul_f32 v[22:23], v[30:31], s[12:13] op_sel_hi:[1,0]
	v_cvt_pk_bf16_f32 v18, v18, v19
	v_pk_mul_f32 v[20:21], v[20:21], v[24:25]
	s_nop 0
	v_permlane32_swap_b32_e32 v16, v18
	v_pk_mul_f32 v[20:21], v[22:23], v[20:21]
	v_mov_b32_e32 v22, v54
	v_cvt_pk_bf16_f32 v19, v20, v21
	s_nop 1
	v_permlane32_swap_b32_e32 v17, v19
	v_permlane32_swap_b32_e32 v52, v22
	global_store_dwordx4 v[76:77], v[16:19], off offset:160
	v_mov_b32_e32 v23, v55
	s_nop 1
	v_permlane32_swap_b32_e32 v53, v23
	v_lshlrev_b32_e32 v16, 16, v52
	v_mul_f32_e32 v17, 0xbfb8aa3b, v16
	v_exp_f32_e32 v18, v17
	v_and_b32_e32 v17, 0xffff0000, v52
	v_mul_f32_e32 v19, 0xbfb8aa3b, v17
	v_exp_f32_e32 v19, v19
	v_lshlrev_b32_e32 v20, 16, v53
	v_and_b32_e32 v21, 0xffff0000, v53
	v_add_f32_e32 v18, 1.0, v18
	v_add_f32_e32 v19, 1.0, v19
	v_mul_f32_e32 v24, 0xbfb8aa3b, v20
	v_mul_f32_e32 v25, 0xbfb8aa3b, v21
	v_rcp_f32_e32 v18, v18
	v_rcp_f32_e32 v19, v19
	v_exp_f32_e32 v24, v24
	v_exp_f32_e32 v25, v25
	v_pk_mul_f32 v[16:17], v[18:19], v[16:17]
	v_add_f32_e32 v18, 1.0, v24
	v_add_f32_e32 v19, 1.0, v25
	v_rcp_f32_e32 v18, v18
	v_rcp_f32_e32 v19, v19
	v_pk_mul_f32 v[0:1], v[0:1], v[16:17]
	v_pk_mul_f32 v[16:17], v[18:19], v[20:21]
	s_nop 0
	v_pk_mul_f32 v[2:3], v[2:3], v[16:17]
	v_cvt_pk_bf16_f32 v0, v0, v1
	v_cvt_pk_bf16_f32 v1, v2, v3
	v_lshlrev_b32_e32 v2, 16, v22
	v_mul_f32_e32 v3, 0xbfb8aa3b, v2
	v_exp_f32_e32 v16, v3
	v_and_b32_e32 v3, 0xffff0000, v22
	v_mul_f32_e32 v17, 0xbfb8aa3b, v3
	v_exp_f32_e32 v17, v17
	v_lshlrev_b32_e32 v18, 16, v23
	v_and_b32_e32 v19, 0xffff0000, v23
	v_add_f32_e32 v16, 1.0, v16
	v_add_f32_e32 v17, 1.0, v17
	v_mul_f32_e32 v20, 0xbfb8aa3b, v18
	v_mul_f32_e32 v21, 0xbfb8aa3b, v19
	v_rcp_f32_e32 v16, v16
	v_rcp_f32_e32 v17, v17
	v_exp_f32_e32 v20, v20
	v_exp_f32_e32 v21, v21
	v_pk_mul_f32 v[2:3], v[16:17], v[2:3]
	v_add_f32_e32 v16, 1.0, v20
	v_add_f32_e32 v17, 1.0, v21
	v_rcp_f32_e32 v16, v16
	v_rcp_f32_e32 v17, v17
	v_pk_mul_f32 v[2:3], v[4:5], v[2:3]
	v_pk_mul_f32 v[4:5], v[6:7], s[12:13] op_sel_hi:[1,0]
	v_cvt_pk_bf16_f32 v2, v2, v3
	v_pk_mul_f32 v[6:7], v[16:17], v[18:19]
	v_mov_b32_e32 v16, v50
	v_pk_mul_f32 v[4:5], v[4:5], v[6:7]
	v_permlane32_swap_b32_e32 v0, v2
	v_cvt_pk_bf16_f32 v3, v4, v5
	s_nop 1
	v_permlane32_swap_b32_e32 v1, v3
	v_permlane32_swap_b32_e32 v48, v16
	global_store_dwordx4 v[76:77], v[0:3], off offset:192
	v_mov_b32_e32 v17, v51
	s_nop 1
	v_permlane32_swap_b32_e32 v49, v17
	v_lshlrev_b32_e32 v0, 16, v48
	v_mul_f32_e32 v1, 0xbfb8aa3b, v0
	v_exp_f32_e32 v2, v1
	v_and_b32_e32 v1, 0xffff0000, v48
	v_mul_f32_e32 v3, 0xbfb8aa3b, v1
	v_exp_f32_e32 v3, v3
	v_lshlrev_b32_e32 v6, 16, v49
	v_and_b32_e32 v7, 0xffff0000, v49
	v_add_f32_e32 v2, 1.0, v2
	v_pk_mul_f32 v[4:5], v[8:9], s[12:13] op_sel_hi:[1,0]
	v_add_f32_e32 v3, 1.0, v3
	v_mul_f32_e32 v8, 0xbfb8aa3b, v6
	v_mul_f32_e32 v9, 0xbfb8aa3b, v7
	v_rcp_f32_e32 v2, v2
	v_rcp_f32_e32 v3, v3
	v_exp_f32_e32 v8, v8
	v_exp_f32_e32 v9, v9
	v_pk_mul_f32 v[0:1], v[2:3], v[0:1]
	v_add_f32_e32 v2, 1.0, v8
	v_add_f32_e32 v3, 1.0, v9
	v_rcp_f32_e32 v2, v2
	v_rcp_f32_e32 v3, v3
	v_pk_mul_f32 v[0:1], v[4:5], v[0:1]
	v_pk_mul_f32 v[4:5], v[10:11], s[12:13] op_sel_hi:[1,0]
	v_cvt_pk_bf16_f32 v0, v0, v1
	v_pk_mul_f32 v[2:3], v[2:3], v[6:7]
	v_lshlrev_b32_e32 v8, 16, v17
	v_pk_mul_f32 v[2:3], v[4:5], v[2:3]
	v_and_b32_e32 v9, 0xffff0000, v17
	v_cvt_pk_bf16_f32 v1, v2, v3
	v_lshlrev_b32_e32 v2, 16, v16
	v_mul_f32_e32 v3, 0xbfb8aa3b, v2
	v_exp_f32_e32 v4, v3
	v_and_b32_e32 v3, 0xffff0000, v16
	v_mul_f32_e32 v5, 0xbfb8aa3b, v3
	v_exp_f32_e32 v5, v5
	v_add_f32_e32 v4, 1.0, v4
	v_mul_f32_e32 v10, 0xbfb8aa3b, v8
	v_mul_f32_e32 v11, 0xbfb8aa3b, v9
	v_add_f32_e32 v5, 1.0, v5
	v_rcp_f32_e32 v4, v4
	v_rcp_f32_e32 v5, v5
	v_exp_f32_e32 v10, v10
	v_exp_f32_e32 v11, v11
	v_pk_mul_f32 v[6:7], v[12:13], s[12:13] op_sel_hi:[1,0]
	v_pk_mul_f32 v[2:3], v[4:5], v[2:3]
	v_add_f32_e32 v4, 1.0, v10
	v_add_f32_e32 v5, 1.0, v11
	v_rcp_f32_e32 v4, v4
	v_rcp_f32_e32 v5, v5
	v_pk_mul_f32 v[2:3], v[6:7], v[2:3]
	v_pk_mul_f32 v[6:7], v[14:15], s[12:13] op_sel_hi:[1,0]
	v_cvt_pk_bf16_f32 v2, v2, v3
	v_pk_mul_f32 v[4:5], v[4:5], v[8:9]
	s_nop 0
	v_permlane32_swap_b32_e32 v0, v2
	v_pk_mul_f32 v[4:5], v[6:7], v[4:5]
	s_nop 0
	v_cvt_pk_bf16_f32 v3, v4, v5
	s_nop 1
	v_permlane32_swap_b32_e32 v1, v3
	global_store_dwordx4 v[76:77], v[0:3], off offset:224

.LBB0_314:
	s_or_b64 exec, exec, s[0:1]
	s_waitcnt lgkmcnt(0)
	s_barrier
	ds_read_b32 v0, v138
	s_mov_b64 s[0:1], -1
	s_waitcnt lgkmcnt(0)
	s_barrier
	v_cmp_lt_i32_e32 vcc, s46, v0
	v_readfirstlane_b32 s4, v0
	s_cbranch_vccnz .LBB0_309
	s_mul_hi_i32 s0, s4, 0x2aaaaaab
	s_lshr_b32 s1, s0, 31
	s_lshr_b32 s0, s0, 2
	s_add_i32 s0, s0, s1
	s_mul_i32 s0, s0, 24
	s_sub_i32 s1, s4, s0
	s_mul_hi_i32 s0, s4, 0xd5555555
	s_lshr_b32 s4, s0, 31
	s_ashr_i32 s38, s0, 2
	s_bfe_i32 s0, s1, 0x80000
	s_mul_i32 s0, s0, 43
	s_add_i32 s38, s38, s4
	s_sext_i32_i16 s4, s0
	s_ashr_i32 s4, s4, 9
	s_bfe_u32 s0, s0, 0x1000f
	s_add_i32 s0, s4, s0
	s_mul_i32 s4, s0, 12
	s_sub_i32 s1, s1, s4
	s_sext_i32_i16 s4, s0
	s_add_i32 s28, s38, 31
	s_mul_hi_i32 s5, s4, 0x7000000
	s_mul_i32 s4, s4, 0x7000000
	s_sext_i32_i8 s1, s1
	s_add_u32 s24, s84, s4
	s_addc_u32 s25, s85, s5
	s_lshl_b32 s4, s1, 7
	s_ashr_i32 s5, s4, 31
	s_lshl_b64 s[26:27], s[4:5], 1
	v_mov_b32_e32 v31, v212
	s_add_u32 s4, s24, s26
	s_addc_u32 s5, s25, s27
	v_readfirstlane_b32 s29, v31
	s_ashr_i32 s1, s29, 6
	s_lshl_b32 s39, s28, 8
	s_lshl_b32 s56, s1, 5
	v_and_b32_e32 v32, 31, v31
	s_add_i32 s56, s56, s39
	v_bfe_u32 v33, v31, 5, 1
	v_or_b32_e32 v122, s56, v32
	v_mov_b64_e32 v[0:1], s[4:5]
	v_mad_i64_i32 v[0:1], s[4:5], v122, s47, v[0:1]
	v_lshlrev_b32_e32 v120, 4, v33
	v_lshl_add_u64 v[0:1], v[0:1], 0, v[120:121]
	s_mov_b64 s[100:101], 0x2400
	v_lshl_add_u64 v[248:249], v[0:1], 0, s[100:101]
	global_load_dwordx4 v[216:219], v[248:249], off
	global_load_dwordx4 v[220:223], v[248:249], off offset:32
	global_load_dwordx4 v[224:227], v[248:249], off offset:64
	global_load_dwordx4 v[228:231], v[248:249], off offset:96
	global_load_dwordx4 v[232:235], v[248:249], off offset:128
	global_load_dwordx4 v[236:239], v[248:249], off offset:160
	global_load_dwordx4 v[240:243], v[248:249], off offset:192
	global_load_dwordx4 v[244:247], v[248:249], off offset:224
	global_load_dwordx4 v[80:83], v[0:1], off
	global_load_dwordx4 v[84:87], v[0:1], off offset:32
	global_load_dwordx4 v[88:91], v[0:1], off offset:64
	global_load_dwordx4 v[92:95], v[0:1], off offset:96
	global_load_dwordx4 v[96:99], v[0:1], off offset:128
	global_load_dwordx4 v[100:103], v[0:1], off offset:160
	global_load_dwordx4 v[104:107], v[0:1], off offset:192
	global_load_dwordx4 v[108:111], v[0:1], off offset:224
	v_mov_b32_e32 v0, s29
	v_bfi_b32 v6, s48, v0, v31
	v_cmp_lt_i32_e32 vcc, s49, v6
	s_and_saveexec_b64 s[4:5], vcc
	s_xor_b64 s[4:5], exec, s[4:5]
	s_cmpk_lt_u32 s29, 0x940
	v_add_u32_e32 v0, 0xfffffbc0, v6
	s_cselect_b64 vcc, -1, 0
	v_cndmask_b32_e32 v0, 0, v0, vcc
	v_mul_hi_u32 v1, v0, s50
	v_lshrrev_b32_e32 v2, 4, v1
	v_mad_u64_u32 v[0:1], s[42:43], v2, s51, v[0:1]
	v_mov_b32_e32 v3, v121
	s_or_saveexec_b64 s[4:5], s[4:5]
	v_mov_b64_e32 v[4:5], 0x1800
	s_xor_b64 exec, exec, s[4:5]
	v_mul_hi_i32 v0, v6, s52
	v_lshrrev_b32_e32 v1, 31, v0
	v_ashrrev_i32_e32 v0, 3, v0
	v_add_u32_e32 v2, v0, v1
	v_mad_u64_u32 v[0:1], s[42:43], v2, s53, v[6:7]
	v_ashrrev_i32_e32 v3, 31, v2
	v_mov_b64_e32 v[4:5], 0xc00
	s_or_b64 exec, exec, s[4:5]
	s_andn2_b32 s29, s29, 63
	v_and_b32_e32 v1, 63, v31
	s_add_i32 s39, s29, 0x200
	v_or_b32_e32 v12, s39, v1
	v_cmp_lt_i32_e32 vcc, s49, v12
	s_and_saveexec_b64 s[4:5], vcc
	s_xor_b64 s[4:5], exec, s[4:5]
	s_cmpk_lt_u32 s39, 0x940
	v_add_u32_e32 v6, 0xfffffbc0, v12
	s_cselect_b64 vcc, -1, 0
	v_cndmask_b32_e32 v6, 0, v6, vcc
	v_mul_hi_u32 v7, v6, s50
	v_lshrrev_b32_e32 v8, 4, v7
	v_mad_u64_u32 v[6:7], s[42:43], v8, s51, v[6:7]
	v_mov_b32_e32 v9, v121
	s_or_saveexec_b64 s[4:5], s[4:5]
	v_mov_b64_e32 v[10:11], 0x1800
	s_xor_b64 exec, exec, s[4:5]
	v_mul_hi_i32 v6, v12, s52
	v_lshrrev_b32_e32 v7, 31, v6
	v_ashrrev_i32_e32 v6, 3, v6
	v_add_u32_e32 v8, v6, v7
	v_mad_u64_u32 v[6:7], s[42:43], v8, s53, v[12:13]
	v_ashrrev_i32_e32 v9, 31, v8
	v_mov_b64_e32 v[10:11], 0xc00
	s_or_b64 exec, exec, s[4:5]
	s_add_i32 s39, s29, 0x400
	v_or_b32_e32 v18, s39, v1
	v_cmp_lt_i32_e32 vcc, s49, v18
	s_and_saveexec_b64 s[4:5], vcc
	s_xor_b64 s[4:5], exec, s[4:5]
	s_cmpk_lt_u32 s39, 0x940
	v_add_u32_e32 v7, 0xfffffbc0, v18
	s_cselect_b64 vcc, -1, 0
	v_cndmask_b32_e32 v12, 0, v7, vcc
	v_mul_hi_u32 v7, v12, s50
	v_lshrrev_b32_e32 v14, 4, v7
	v_mad_u64_u32 v[12:13], s[42:43], v14, s51, v[12:13]
	v_mov_b32_e32 v15, v121
	s_or_saveexec_b64 s[4:5], s[4:5]
	v_mov_b64_e32 v[16:17], 0x1800
	s_xor_b64 exec, exec, s[4:5]
	v_mul_hi_i32 v7, v18, s52
	v_lshrrev_b32_e32 v12, 31, v7
	v_ashrrev_i32_e32 v7, 3, v7
	v_add_u32_e32 v14, v7, v12
	v_mad_u64_u32 v[12:13], s[42:43], v14, s53, v[18:19]
	v_ashrrev_i32_e32 v15, 31, v14
	v_mov_b64_e32 v[16:17], 0xc00
	s_or_b64 exec, exec, s[4:5]
	s_add_i32 s39, s29, 0x600
	v_or_b32_e32 v18, s39, v1
	v_cmp_lt_i32_e32 vcc, s49, v18
	s_and_saveexec_b64 s[4:5], vcc
	s_xor_b64 s[4:5], exec, s[4:5]
	s_cmpk_lt_u32 s39, 0x940
	v_add_u32_e32 v7, 0xfffffbc0, v18
	s_cselect_b64 vcc, -1, 0
	v_cndmask_b32_e32 v18, 0, v7, vcc
	v_mul_hi_u32 v7, v18, s50
	v_lshrrev_b32_e32 v24, 4, v7
	v_mad_u64_u32 v[22:23], s[42:43], v24, s51, v[18:19]
	v_mov_b32_e32 v25, v121
	s_or_saveexec_b64 s[4:5], s[4:5]
	v_mov_b64_e32 v[28:29], 0x1800
	s_xor_b64 exec, exec, s[4:5]
	v_mul_hi_i32 v7, v18, s52
	v_lshrrev_b32_e32 v13, 31, v7
	v_ashrrev_i32_e32 v7, 3, v7
	v_add_u32_e32 v24, v7, v13
	v_mad_u64_u32 v[22:23], s[42:43], v24, s53, v[18:19]
	v_ashrrev_i32_e32 v25, 31, v24
	v_mov_b64_e32 v[28:29], 0xc00
	s_or_b64 exec, exec, s[4:5]
	s_addk_i32 s29, 0x800
	v_or_b32_e32 v30, s29, v1
	v_cmp_lt_i32_e32 vcc, s49, v30
	s_and_saveexec_b64 s[4:5], vcc
	s_xor_b64 s[4:5], exec, s[4:5]
	s_cmpk_lt_u32 s29, 0x940
	v_add_u32_e32 v7, 0xfffffbc0, v30
	s_cselect_b64 vcc, -1, 0
	v_cndmask_b32_e32 v18, 0, v7, vcc
	v_mul_hi_u32 v7, v18, s50
	v_lshrrev_b32_e32 v20, 4, v7
	v_mad_u64_u32 v[18:19], s[42:43], v20, s51, v[18:19]
	v_mov_b32_e32 v21, v121
	s_or_saveexec_b64 s[4:5], s[4:5]
	v_mov_b64_e32 v[26:27], 0x1800
	s_xor_b64 exec, exec, s[4:5]
	v_mul_hi_i32 v7, v30, s52
	v_lshrrev_b32_e32 v13, 31, v7
	v_ashrrev_i32_e32 v7, 3, v7
	v_add_u32_e32 v20, v7, v13
	v_mad_u64_u32 v[18:19], s[42:43], v20, s53, v[30:31]
	v_ashrrev_i32_e32 v21, 31, v20
	v_mov_b64_e32 v[26:27], 0xc00
	s_or_b64 exec, exec, s[4:5]
	v_lshl_add_u64 v[4:5], s[24:25], 0, v[4:5]
	v_lshl_add_u64 v[4:5], v[4:5], 0, s[26:27]
	v_lshlrev_b32_e32 v7, 3, v22
	v_cmp_gt_i32_e32 vcc, 16, v22
	v_mad_u64_u32 v[4:5], s[4:5], v2, s47, v[4:5]
	s_nop 0
	v_cndmask_b32_e32 v22, 0, v7, vcc
	v_lshlrev_b32_e32 v7, 3, v12
	v_cmp_gt_i32_e32 vcc, 16, v12
	v_mov_b32_e32 v2, v5
	v_mad_u64_u32 v[2:3], s[4:5], v3, s47, v[2:3]
	v_cndmask_b32_e32 v12, 0, v7, vcc
	v_lshlrev_b32_e32 v7, 3, v6
	v_cmp_gt_i32_e32 vcc, 16, v6
	v_mov_b32_e32 v5, v2
	v_lshlrev_b32_e32 v2, 3, v0
	v_cndmask_b32_e32 v6, 0, v7, vcc
	v_cmp_gt_i32_e32 vcc, 16, v0
	v_lshl_add_u64 v[28:29], s[24:25], 0, v[28:29]
	v_lshl_add_u64 v[16:17], s[24:25], 0, v[16:17]
	v_cndmask_b32_e32 v2, 0, v2, vcc
	v_ashrrev_i32_e32 v3, 31, v2
	v_lshl_add_u64 v[10:11], s[24:25], 0, v[10:11]
	v_lshl_add_u64 v[130:131], v[2:3], 1, v[4:5]
	v_lshl_add_u64 v[2:3], s[24:25], 0, v[26:27]
	v_lshl_add_u64 v[28:29], v[28:29], 0, s[26:27]
	v_lshl_add_u64 v[16:17], v[16:17], 0, s[26:27]
	v_lshl_add_u64 v[10:11], v[10:11], 0, s[26:27]
	v_lshl_add_u64 v[2:3], v[2:3], 0, s[26:27]
	v_mad_u64_u32 v[28:29], s[4:5], v24, s47, v[28:29]
	v_mad_u64_u32 v[16:17], s[4:5], v14, s47, v[16:17]
	v_mad_u64_u32 v[10:11], s[4:5], v8, s47, v[10:11]
	v_mad_u64_u32 v[2:3], s[4:5], v20, s47, v[2:3]
	v_mov_b32_e32 v24, v29
	v_mov_b32_e32 v14, v17
	v_mov_b32_e32 v8, v11
	v_mov_b32_e32 v0, v3
	v_mad_u64_u32 v[24:25], s[4:5], v25, s47, v[24:25]
	v_mad_u64_u32 v[14:15], s[4:5], v15, s47, v[14:15]
	v_mad_u64_u32 v[8:9], s[4:5], v9, s47, v[8:9]
	v_mad_u64_u32 v[4:5], s[4:5], v21, s47, v[0:1]
	v_lshlrev_b32_e32 v0, 3, v18
	v_cmp_gt_i32_e32 vcc, 16, v18
	s_lshl_b32 s58, s28, 2
	v_mov_b32_e32 v3, v4
	v_cndmask_b32_e32 v4, 0, v0, vcc
	s_lshl_b32 s4, s1, 10
	v_mov_b32_e32 v11, v8
	v_ashrrev_i32_e32 v7, 31, v6
	v_ashrrev_i32_e32 v5, 31, v4
	s_or_b32 s28, s58, 3
	s_add_i32 s57, s4, 0
	v_mov_b32_e32 v17, v14
	v_ashrrev_i32_e32 v13, 31, v12
	v_lshl_add_u64 v[128:129], v[6:7], 1, v[10:11]
	v_lshl_add_u64 v[132:133], v[4:5], 1, v[2:3]
	v_mad_u64_u32 v[2:3], s[4:5], s28, v139, v[130:131]
	s_mov_b32 m0, s57
	v_mov_b32_e32 v29, v24
	v_ashrrev_i32_e32 v23, 31, v22
	v_lshl_add_u64 v[126:127], v[12:13], 1, v[16:17]
	global_load_lds_dwordx4 v[2:3], off
	v_mad_u64_u32 v[2:3], s[4:5], s28, v139, v[128:129]
	s_add_i32 m0, s57, 0x2000
	v_lshl_add_u64 v[124:125], v[22:23], 1, v[28:29]
	global_load_lds_dwordx4 v[2:3], off
	v_mad_u64_u32 v[2:3], s[4:5], s28, v139, v[126:127]
	s_add_i32 m0, s57, 0x4000
	s_nop 0
	global_load_lds_dwordx4 v[2:3], off
	v_mad_u64_u32 v[2:3], s[4:5], s28, v139, v[124:125]
	s_add_i32 m0, s57, 0x6000
	s_nop 0
	global_load_lds_dwordx4 v[2:3], off
	v_mad_u64_u32 v[2:3], s[4:5], s28, v139, v[132:133]
	s_add_i32 m0, s57, 0x8000
	s_or_b32 s28, s58, 2
	global_load_lds_dwordx4 v[2:3], off
	s_add_i32 m0, s57, 0xa000
	v_mad_u64_u32 v[2:3], s[4:5], s28, v139, v[130:131]
	global_load_lds_dwordx4 v[2:3], off
	v_mad_u64_u32 v[2:3], s[4:5], s28, v139, v[128:129]
	s_add_i32 m0, s57, 0xc000
	s_nop 0
	global_load_lds_dwordx4 v[2:3], off
	v_mad_u64_u32 v[2:3], s[4:5], s28, v139, v[126:127]
	s_add_i32 m0, s57, 0xe000
	s_nop 0
	global_load_lds_dwordx4 v[2:3], off
	v_mad_u64_u32 v[2:3], s[4:5], s28, v139, v[124:125]
	s_add_i32 m0, s57, 0x10000
	s_nop 0
	global_load_lds_dwordx4 v[2:3], off
	v_mad_u64_u32 v[2:3], s[4:5], s28, v139, v[132:133]
	s_add_i32 m0, s57, 0x12000
	s_cmp_lt_i32 s1, 4
	global_load_lds_dwordx4 v[2:3], off
	s_cbranch_scc1 .LBB0_337
	s_setprio 1

	.amdhsa_kernel _ZN2mk3fwdENS_4ArgsE
		.amdhsa_group_segment_fixed_size 0
		.amdhsa_private_segment_fixed_size 0
		.amdhsa_kernarg_size 464
		.amdhsa_user_sgpr_count 2
		.amdhsa_user_sgpr_dispatch_ptr 0
		.amdhsa_user_sgpr_queue_ptr 0
		.amdhsa_user_sgpr_kernarg_segment_ptr 1
		.amdhsa_user_sgpr_dispatch_id 0
		.amdhsa_user_sgpr_kernarg_preload_length 0
		.amdhsa_user_sgpr_kernarg_preload_offset 0
		.amdhsa_user_sgpr_private_segment_size 0
		.amdhsa_uses_dynamic_stack 0
		.amdhsa_enable_private_segment 0
		.amdhsa_system_sgpr_workgroup_id_x 1
		.amdhsa_system_sgpr_workgroup_id_y 0
		.amdhsa_system_sgpr_workgroup_id_z 0
		.amdhsa_system_sgpr_workgroup_info 0
		.amdhsa_system_vgpr_workitem_id 2
		.amdhsa_next_free_vgpr 255
		.amdhsa_next_free_sgpr 102
		.amdhsa_accum_offset 256
		.amdhsa_reserve_vcc 1
		.amdhsa_float_round_mode_32 0
		.amdhsa_float_round_mode_16_64 0
		.amdhsa_float_denorm_mode_32 3
		.amdhsa_float_denorm_mode_16_64 3
		.amdhsa_dx10_clamp 1
		.amdhsa_ieee_mode 1
		.amdhsa_fp16_overflow 0
		.amdhsa_tg_split 0
		.amdhsa_exception_fp_ieee_invalid_op 0
		.amdhsa_exception_fp_denorm_src 0
		.amdhsa_exception_fp_ieee_div_zero 0
		.amdhsa_exception_fp_ieee_overflow 0
		.amdhsa_exception_fp_ieee_underflow 0
		.amdhsa_exception_fp_ieee_inexact 0
		.amdhsa_exception_int_div_zero 0
	.end_amdhsa_kernel

amdhsa.kernels:
  - .agpr_count:     0
    .args:
      - .offset:         0
        .size:           208
        .value_kind:     by_value
      - .offset:         208
        .size:           4
        .value_kind:     hidden_block_count_x
      - .offset:         212
        .size:           4
        .value_kind:     hidden_block_count_y
      - .offset:         216
        .size:           4
        .value_kind:     hidden_block_count_z
      - .offset:         220
        .size:           2
        .value_kind:     hidden_group_size_x
      - .offset:         222
        .size:           2
        .value_kind:     hidden_group_size_y
      - .offset:         224
        .size:           2
        .value_kind:     hidden_group_size_z
      - .offset:         226
        .size:           2
        .value_kind:     hidden_remainder_x
      - .offset:         228
        .size:           2
        .value_kind:     hidden_remainder_y
      - .offset:         230
        .size:           2
        .value_kind:     hidden_remainder_z
      - .offset:         248
        .size:           8
        .value_kind:     hidden_global_offset_x
      - .offset:         256
        .size:           8
        .value_kind:     hidden_global_offset_y
      - .offset:         264
        .size:           8
        .value_kind:     hidden_global_offset_z
      - .offset:         272
        .size:           2
        .value_kind:     hidden_grid_dims
      - .offset:         296
        .size:           8
        .value_kind:     hidden_multigrid_sync_arg
      - .offset:         328
        .size:           4
        .value_kind:     hidden_dynamic_lds_size
    .group_segment_fixed_size: 0
    .kernarg_segment_align: 8
    .kernarg_segment_size: 464
    .language:       OpenCL C
    .language_version:
      - 2
      - 0
    .max_flat_workgroup_size: 512
    .name:           _ZN2mk3fwdENS_4ArgsE
    .private_segment_fixed_size: 0
    .sgpr_count:     108
    .sgpr_spill_count: 59
    .symbol:         _ZN2mk3fwdENS_4ArgsE.kd
    .uniform_work_group_size: 1
    .uses_dynamic_stack: false
    .vgpr_count:     255
    .vgpr_spill_count: 0
    .wavefront_size: 64
